# v3 plus: SwiGLU epilogue stores sc1 (write-through)
# speedup vs baseline: 1.0273x; 1.0273x over previous
.LBB0_356:
	s_lshl_b32 s1, s39, 2
	s_add_i32 s1, s0, s1
	v_cvt_f32_i32_e32 v168, v96
	v_cvt_f32_i32_e32 v96, v70
	v_cvt_f32_i32_e32 v70, v22
	v_cvt_f32_i32_e32 v22, v2
	v_lshl_add_u32 v2, v149, 2, s1
	s_lshl_b32 s1, s40, 2
	s_add_i32 s0, s0, s1
	v_cvt_f32_i32_e32 v161, v127
	v_cvt_f32_i32_e32 v160, v126
	v_cvt_f32_i32_e32 v163, v129
	v_cvt_f32_i32_e32 v162, v128
	v_cvt_f32_i32_e32 v167, v125
	v_cvt_f32_i32_e32 v166, v124
	v_cvt_f32_i32_e32 v125, v115
	v_cvt_f32_i32_e32 v124, v114
	v_cvt_f32_i32_e32 v173, v93
	v_cvt_f32_i32_e32 v172, v92
	v_cvt_f32_i32_e32 v177, v87
	v_cvt_f32_i32_e32 v176, v86
	v_cvt_f32_i32_e32 v93, v73
	v_cvt_f32_i32_e32 v92, v72
	v_cvt_f32_i32_e32 v87, v27
	v_cvt_f32_i32_e32 v86, v26
	ds_read2_b32 v[178:179], v2 offset1:16
	ds_read2_b32 v[114:115], v2 offset0:32 offset1:48
	ds_read2_b32 v[72:73], v2 offset0:128 offset1:144
	ds_read2_b32 v[26:27], v2 offset0:160 offset1:176
	v_lshl_add_u32 v2, v151, 2, s0
	v_cvt_f32_i32_e32 v165, v123
	v_cvt_f32_i32_e32 v164, v122
	v_cvt_f32_i32_e32 v129, v119
	v_cvt_f32_i32_e32 v128, v118
	v_cvt_f32_i32_e32 v137, v121
	v_cvt_f32_i32_e32 v136, v120
	v_cvt_f32_i32_e32 v127, v117
	v_cvt_f32_i32_e32 v126, v116
	v_cvt_f32_i32_e32 v169, v97
	v_cvt_f32_i32_e32 v171, v95
	v_cvt_f32_i32_e32 v170, v94
	v_cvt_f32_i32_e32 v175, v91
	v_cvt_f32_i32_e32 v174, v90
	v_cvt_f32_i32_e32 v139, v85
	v_cvt_f32_i32_e32 v138, v84
	v_cvt_f32_i32_e32 v119, v81
	v_cvt_f32_i32_e32 v118, v80
	v_cvt_f32_i32_e32 v123, v79
	v_cvt_f32_i32_e32 v122, v78
	v_cvt_f32_i32_e32 v117, v77
	v_cvt_f32_i32_e32 v116, v76
	v_cvt_f32_i32_e32 v121, v75
	v_cvt_f32_i32_e32 v120, v74
	v_cvt_f32_i32_e32 v97, v71
	v_cvt_f32_i32_e32 v91, v69
	v_cvt_f32_i32_e32 v90, v68
	v_cvt_f32_i32_e32 v95, v67
	v_cvt_f32_i32_e32 v94, v66
	v_cvt_f32_i32_e32 v79, v63
	v_cvt_f32_i32_e32 v78, v62
	v_cvt_f32_i32_e32 v81, v65
	v_cvt_f32_i32_e32 v80, v64
	v_cvt_f32_i32_e32 v75, v59
	v_cvt_f32_i32_e32 v74, v58
	v_cvt_f32_i32_e32 v77, v61
	v_cvt_f32_i32_e32 v76, v60
	v_cvt_f32_i32_e32 v61, v55
	v_cvt_f32_i32_e32 v60, v54
	v_cvt_f32_i32_e32 v63, v57
	v_cvt_f32_i32_e32 v62, v56
	v_cvt_f32_i32_e32 v57, v51
	v_cvt_f32_i32_e32 v56, v50
	v_cvt_f32_i32_e32 v59, v53
	v_cvt_f32_i32_e32 v58, v52
	v_cvt_f32_i32_e32 v85, v33
	v_cvt_f32_i32_e32 v84, v32
	v_cvt_f32_i32_e32 v67, v25
	v_cvt_f32_i32_e32 v66, v24
	v_cvt_f32_i32_e32 v71, v23
	v_cvt_f32_i32_e32 v65, v21
	v_cvt_f32_i32_e32 v64, v20
	v_cvt_f32_i32_e32 v69, v19
	v_cvt_f32_i32_e32 v68, v18
	v_cvt_f32_i32_e32 v51, v17
	v_cvt_f32_i32_e32 v50, v16
	v_cvt_f32_i32_e32 v55, v15
	v_cvt_f32_i32_e32 v54, v14
	v_cvt_f32_i32_e32 v33, v13
	v_cvt_f32_i32_e32 v32, v12
	v_cvt_f32_i32_e32 v53, v11
	v_cvt_f32_i32_e32 v52, v10
	v_cvt_f32_i32_e32 v21, v9
	v_cvt_f32_i32_e32 v20, v8
	v_cvt_f32_i32_e32 v25, v7
	v_cvt_f32_i32_e32 v24, v6
	v_cvt_f32_i32_e32 v19, v5
	v_cvt_f32_i32_e32 v18, v4
	v_cvt_f32_i32_e32 v23, v3
	ds_read_b128 v[14:17], v2 offset:1024
	ds_read_b128 v[10:13], v2 offset:1040
	ds_read_b128 v[6:9], v2 offset:1536
	ds_read_b128 v[2:5], v2 offset:1552
	v_cvt_f32_i32_e32 v140, v88
	s_waitcnt lgkmcnt(0)
	v_pk_mul_f32 v[162:163], v[16:17], v[162:163]
	v_pk_mul_f32 v[160:161], v[14:15], v[160:161]
	v_pk_mul_f32 v[162:163], v[178:179], v[162:163] op_sel_hi:[0,1]
	v_pk_mul_f32 v[160:161], v[178:179], v[160:161] op_sel_hi:[0,1]
	v_pk_mul_f32 v[164:165], v[10:11], v[164:165]
	v_pk_mul_f32 v[170:171], v[6:7], v[170:171]
	v_pk_mul_f32 v[166:167], v[12:13], v[166:167]
	v_pk_mul_f32 v[164:165], v[178:179], v[164:165] op_sel_hi:[0,1]
	v_pk_mul_f32 v[168:169], v[8:9], v[168:169]
	v_pk_mul_f32 v[170:171], v[178:179], v[170:171] op_sel_hi:[0,1]
	v_pk_mul_f32 v[182:183], v[162:163], s[26:27] op_sel_hi:[1,0]
	v_pk_mul_f32 v[184:185], v[160:161], s[26:27] op_sel_hi:[1,0]
	v_pk_mul_f32 v[166:167], v[178:179], v[166:167] op_sel_hi:[0,1]
	v_pk_mul_f32 v[168:169], v[178:179], v[168:169] op_sel_hi:[0,1]
	v_exp_f32_e32 v184, v184
	v_exp_f32_e32 v182, v182
	v_exp_f32_e32 v183, v183
	v_exp_f32_e32 v185, v185
	v_pk_mul_f32 v[160:161], v[160:161], v[170:171]
	v_pk_mul_f32 v[170:171], v[164:165], s[26:27] op_sel_hi:[1,0]
	v_pk_mul_f32 v[162:163], v[162:163], v[168:169]
	v_pk_mul_f32 v[168:169], v[166:167], s[26:27] op_sel_hi:[1,0]
	v_exp_f32_e32 v170, v170
	v_exp_f32_e32 v171, v171
	v_exp_f32_e32 v168, v168
	v_exp_f32_e32 v169, v169
	v_pk_add_f32 v[182:183], v[182:183], 1.0 op_sel_hi:[1,0]
	v_pk_add_f32 v[184:185], v[184:185], 1.0 op_sel_hi:[1,0]
	v_rcp_f32_e32 v182, v182
	v_rcp_f32_e32 v184, v184
	v_rcp_f32_e32 v185, v185
	v_rcp_f32_e32 v183, v183
	v_pk_add_f32 v[170:171], v[170:171], 1.0 op_sel_hi:[1,0]
	v_pk_add_f32 v[168:169], v[168:169], 1.0 op_sel_hi:[1,0]
	v_rcp_f32_e32 v170, v170
	v_rcp_f32_e32 v171, v171
	v_cvt_f32_i32_e32 v88, v30
	v_lshl_or_b32 v30, s60, 7, v152
	v_pk_mul_f32 v[174:175], v[2:3], v[174:175]
	v_rcp_f32_e32 v168, v168
	v_rcp_f32_e32 v169, v169
	v_cvt_f32_i32_e32 v141, v89
	v_cvt_f32_i32_e32 v143, v83
	v_cvt_f32_i32_e32 v142, v82
	v_cvt_f32_i32_e32 v89, v31
	v_cvt_f32_i32_e32 v83, v29
	v_cvt_f32_i32_e32 v82, v28
	v_lshl_add_u32 v158, s61, 8, v150
	v_ashrrev_i32_e32 v31, 31, v30
	v_mov_b64_e32 v[28:29], s[20:21]
	v_pk_mul_f32 v[172:173], v[4:5], v[172:173]
	v_pk_mul_f32 v[174:175], v[178:179], v[174:175] op_sel_hi:[0,1]
	v_mad_i64_i32 v[180:181], s[0:1], v158, s52, v[28:29]
	v_lshlrev_b64 v[30:31], 1, v[30:31]
	v_pk_mul_f32 v[172:173], v[178:179], v[172:173] op_sel_hi:[0,1]
	v_pk_mul_f32 v[162:163], v[162:163], v[182:183]
	v_pk_mul_f32 v[160:161], v[160:161], v[184:185]
	v_pk_mul_f32 v[164:165], v[164:165], v[174:175]
	v_lshl_add_u64 v[180:181], v[180:181], 0, v[30:31]
	v_pk_mul_f32 v[166:167], v[166:167], v[172:173]
	v_pk_mul_f32 v[164:165], v[164:165], v[170:171]
	v_cvt_pk_bf16_f32 v160, v160, v161
	v_cvt_pk_bf16_f32 v161, v162, v163
	v_pk_mul_f32 v[166:167], v[166:167], v[168:169]
	v_cvt_pk_bf16_f32 v162, v164, v165
	v_pk_mul_f32 v[136:137], v[16:17], v[136:137]
	v_cvt_pk_bf16_f32 v163, v166, v167
	global_store_dwordx4 v[180:181], v[160:163], off sc1
	v_pk_mul_f32 v[128:129], v[14:15], v[128:129]
	v_pk_mul_f32 v[126:127], v[12:13], v[126:127]
	v_mov_b32_e32 v162, v179
	v_pk_mul_f32 v[136:137], v[162:163], v[136:137] op_sel_hi:[0,1]
	v_pk_mul_f32 v[166:167], v[136:137], s[26:27] op_sel_hi:[1,0]
	v_pk_mul_f32 v[124:125], v[10:11], v[124:125]
	v_exp_f32_e32 v166, v166
	v_exp_f32_e32 v167, v167
	v_pk_mul_f32 v[164:165], v[6:7], v[176:177]
	v_pk_mul_f32 v[140:141], v[8:9], v[140:141]
	v_pk_mul_f32 v[128:129], v[162:163], v[128:129] op_sel_hi:[0,1]
	v_pk_mul_f32 v[124:125], v[162:163], v[124:125] op_sel_hi:[0,1]
	v_pk_mul_f32 v[126:127], v[162:163], v[126:127] op_sel_hi:[0,1]
	v_pk_mul_f32 v[140:141], v[162:163], v[140:141] op_sel_hi:[0,1]
	v_pk_mul_f32 v[164:165], v[162:163], v[164:165] op_sel_hi:[0,1]
	v_pk_mul_f32 v[142:143], v[2:3], v[142:143]
	v_pk_mul_f32 v[138:139], v[4:5], v[138:139]
	v_pk_mul_f32 v[168:169], v[128:129], s[26:27] op_sel_hi:[1,0]
	v_pk_mul_f32 v[138:139], v[162:163], v[138:139] op_sel_hi:[0,1]
	v_pk_mul_f32 v[142:143], v[162:163], v[142:143] op_sel_hi:[0,1]
	v_pk_add_f32 v[162:163], v[166:167], 1.0 op_sel_hi:[1,0]
	v_pk_mul_f32 v[128:129], v[128:129], v[164:165]
	v_pk_mul_f32 v[136:137], v[136:137], v[140:141]
	v_pk_mul_f32 v[140:141], v[126:127], s[26:27] op_sel_hi:[1,0]
	v_pk_mul_f32 v[164:165], v[124:125], s[26:27] op_sel_hi:[1,0]
	v_rcp_f32_e32 v162, v162
	v_rcp_f32_e32 v163, v163
	v_exp_f32_e32 v164, v164
	v_exp_f32_e32 v140, v140
	v_exp_f32_e32 v141, v141
	v_exp_f32_e32 v165, v165
	v_exp_f32_e32 v168, v168
	v_exp_f32_e32 v169, v169
	v_pk_mul_f32 v[136:137], v[136:137], v[162:163]
	v_pk_add_f32 v[140:141], v[140:141], 1.0 op_sel_hi:[1,0]
	v_pk_add_f32 v[162:163], v[164:165], 1.0 op_sel_hi:[1,0]
	v_cvt_f32_i32_e32 v111, v111
	v_cvt_f32_i32_e32 v110, v110
	v_cvt_f32_i32_e32 v113, v113
	v_cvt_f32_i32_e32 v112, v112
	v_cvt_f32_i32_e32 v107, v107
	v_cvt_f32_i32_e32 v106, v106
	v_cvt_f32_i32_e32 v109, v109
	v_cvt_f32_i32_e32 v108, v108
	v_pk_add_f32 v[166:167], v[168:169], 1.0 op_sel_hi:[1,0]
	v_rcp_f32_e32 v162, v162
	v_rcp_f32_e32 v140, v140
	v_rcp_f32_e32 v141, v141
	v_rcp_f32_e32 v163, v163
	v_rcp_f32_e32 v166, v166
	v_rcp_f32_e32 v167, v167
	v_or_b32_e32 v159, 16, v158
	v_pk_mul_f32 v[124:125], v[124:125], v[142:143]
	v_pk_mul_f32 v[126:127], v[126:127], v[138:139]
	v_mad_i64_i32 v[160:161], s[0:1], v159, s52, v[28:29]
	v_pk_mul_f32 v[138:139], v[126:127], v[140:141]
	v_pk_mul_f32 v[126:127], v[124:125], v[162:163]
	v_pk_mul_f32 v[112:113], v[16:17], v[112:113]
	v_pk_mul_f32 v[110:111], v[14:15], v[110:111]
	v_pk_mul_f32 v[108:109], v[12:13], v[108:109]
	v_pk_mul_f32 v[106:107], v[10:11], v[106:107]
	v_pk_mul_f32 v[122:123], v[6:7], v[122:123]
	v_pk_mul_f32 v[118:119], v[8:9], v[118:119]
	v_lshl_add_u64 v[160:161], v[160:161], 0, v[30:31]
	v_pk_mul_f32 v[128:129], v[128:129], v[166:167]
	v_pk_mul_f32 v[110:111], v[114:115], v[110:111] op_sel_hi:[0,1]
	v_cvt_pk_bf16_f32 v124, v128, v129
	v_cvt_pk_bf16_f32 v125, v136, v137
	v_cvt_pk_bf16_f32 v126, v126, v127
	v_cvt_pk_bf16_f32 v127, v138, v139
	v_pk_mul_f32 v[112:113], v[114:115], v[112:113] op_sel_hi:[0,1]
	v_pk_mul_f32 v[106:107], v[114:115], v[106:107] op_sel_hi:[0,1]
	v_pk_mul_f32 v[108:109], v[114:115], v[108:109] op_sel_hi:[0,1]
	v_pk_mul_f32 v[118:119], v[114:115], v[118:119] op_sel_hi:[0,1]
	v_pk_mul_f32 v[122:123], v[114:115], v[122:123] op_sel_hi:[0,1]
	global_store_dwordx4 v[160:161], v[124:127], off sc1
	v_pk_mul_f32 v[128:129], v[110:111], s[26:27] op_sel_hi:[1,0]
	v_pk_mul_f32 v[110:111], v[110:111], v[122:123]
	v_pk_mul_f32 v[126:127], v[112:113], s[26:27] op_sel_hi:[1,0]
	v_pk_mul_f32 v[112:113], v[112:113], v[118:119]
	v_pk_mul_f32 v[118:119], v[108:109], s[26:27] op_sel_hi:[1,0]
	v_pk_mul_f32 v[122:123], v[106:107], s[26:27] op_sel_hi:[1,0]
	v_exp_f32_e32 v118, v118
	v_exp_f32_e32 v122, v122
	v_exp_f32_e32 v119, v119
	v_exp_f32_e32 v123, v123
	v_exp_f32_e32 v128, v128
	v_exp_f32_e32 v126, v126
	v_exp_f32_e32 v127, v127
	v_exp_f32_e32 v129, v129
	v_pk_add_f32 v[118:119], v[118:119], 1.0 op_sel_hi:[1,0]
	v_pk_add_f32 v[122:123], v[122:123], 1.0 op_sel_hi:[1,0]
	v_pk_add_f32 v[126:127], v[126:127], 1.0 op_sel_hi:[1,0]
	v_pk_add_f32 v[128:129], v[128:129], 1.0 op_sel_hi:[1,0]
	v_rcp_f32_e32 v122, v122
	v_rcp_f32_e32 v118, v118
	v_rcp_f32_e32 v119, v119
	v_rcp_f32_e32 v123, v123
	v_pk_mul_f32 v[120:121], v[2:3], v[120:121]
	v_pk_mul_f32 v[116:117], v[4:5], v[116:117]
	v_rcp_f32_e32 v128, v128
	v_rcp_f32_e32 v129, v129
	v_rcp_f32_e32 v126, v126
	v_rcp_f32_e32 v127, v127
	v_cvt_f32_i32_e32 v105, v105
	v_cvt_f32_i32_e32 v104, v104
	v_pk_mul_f32 v[116:117], v[114:115], v[116:117] op_sel_hi:[0,1]
	v_pk_mul_f32 v[120:121], v[114:115], v[120:121] op_sel_hi:[0,1]
	v_cvt_f32_i32_e32 v103, v103
	v_cvt_f32_i32_e32 v102, v102
	v_cvt_f32_i32_e32 v99, v99
	v_cvt_f32_i32_e32 v98, v98
	v_cvt_f32_i32_e32 v101, v101
	v_cvt_f32_i32_e32 v100, v100
	v_or_b32_e32 v124, 32, v158
	v_pk_mul_f32 v[106:107], v[106:107], v[120:121]
	v_pk_mul_f32 v[108:109], v[108:109], v[116:117]
	v_mad_i64_i32 v[124:125], s[0:1], v124, s52, v[28:29]
	v_pk_mul_f32 v[116:117], v[108:109], v[118:119]
	v_pk_mul_f32 v[108:109], v[106:107], v[122:123]
	v_lshl_add_u64 v[124:125], v[124:125], 0, v[30:31]
	v_pk_mul_f32 v[112:113], v[112:113], v[126:127]
	v_pk_mul_f32 v[110:111], v[110:111], v[128:129]
	v_pk_mul_f32 v[104:105], v[16:17], v[104:105]
	v_cvt_pk_bf16_f32 v106, v110, v111
	v_cvt_pk_bf16_f32 v107, v112, v113
	v_cvt_pk_bf16_f32 v108, v108, v109
	v_cvt_pk_bf16_f32 v109, v116, v117
	global_store_dwordx4 v[124:125], v[106:109], off sc1
	v_pk_mul_f32 v[102:103], v[14:15], v[102:103]
	v_pk_mul_f32 v[100:101], v[12:13], v[100:101]
	v_mov_b32_e32 v108, v115
	v_pk_mul_f32 v[104:105], v[108:109], v[104:105] op_sel_hi:[0,1]
	v_pk_mul_f32 v[98:99], v[10:11], v[98:99]
	v_pk_mul_f32 v[96:97], v[6:7], v[96:97]
	v_pk_mul_f32 v[92:93], v[8:9], v[92:93]
	v_pk_mul_f32 v[102:103], v[108:109], v[102:103] op_sel_hi:[0,1]
	v_pk_mul_f32 v[98:99], v[108:109], v[98:99] op_sel_hi:[0,1]
	v_pk_mul_f32 v[100:101], v[108:109], v[100:101] op_sel_hi:[0,1]
	v_pk_mul_f32 v[92:93], v[108:109], v[92:93] op_sel_hi:[0,1]
	v_pk_mul_f32 v[96:97], v[108:109], v[96:97] op_sel_hi:[0,1]
	v_pk_mul_f32 v[110:111], v[104:105], s[26:27] op_sel_hi:[1,0]
	v_pk_mul_f32 v[112:113], v[102:103], s[26:27] op_sel_hi:[1,0]
	v_exp_f32_e32 v110, v110
	v_exp_f32_e32 v111, v111
	v_pk_mul_f32 v[96:97], v[102:103], v[96:97]
	v_pk_mul_f32 v[92:93], v[104:105], v[92:93]
	v_pk_mul_f32 v[102:103], v[100:101], s[26:27] op_sel_hi:[1,0]
	v_pk_mul_f32 v[104:105], v[98:99], s[26:27] op_sel_hi:[1,0]
	v_exp_f32_e32 v112, v112
	v_exp_f32_e32 v113, v113
	v_exp_f32_e32 v104, v104
	v_exp_f32_e32 v102, v102
	v_exp_f32_e32 v103, v103
	v_exp_f32_e32 v105, v105
	v_pk_mul_f32 v[94:95], v[2:3], v[94:95]
	v_pk_mul_f32 v[90:91], v[4:5], v[90:91]
	v_pk_mul_f32 v[94:95], v[108:109], v[94:95] op_sel_hi:[0,1]
	v_pk_mul_f32 v[90:91], v[108:109], v[90:91] op_sel_hi:[0,1]
	v_pk_add_f32 v[108:109], v[110:111], 1.0 op_sel_hi:[1,0]
	v_pk_add_f32 v[110:111], v[112:113], 1.0 op_sel_hi:[1,0]
	v_rcp_f32_e32 v108, v108
	v_rcp_f32_e32 v109, v109
	v_pk_add_f32 v[102:103], v[102:103], 1.0 op_sel_hi:[1,0]
	v_pk_add_f32 v[104:105], v[104:105], 1.0 op_sel_hi:[1,0]
	v_rcp_f32_e32 v110, v110
	v_rcp_f32_e32 v111, v111
	v_rcp_f32_e32 v104, v104
	v_rcp_f32_e32 v102, v102
	v_rcp_f32_e32 v103, v103
	v_rcp_f32_e32 v105, v105
	v_or_b32_e32 v106, 48, v158
	v_mad_i64_i32 v[106:107], s[0:1], v106, s52, v[28:29]
	v_pk_mul_f32 v[92:93], v[92:93], v[108:109]
	v_pk_mul_f32 v[94:95], v[98:99], v[94:95]
	v_pk_mul_f32 v[90:91], v[100:101], v[90:91]
	v_pk_mul_f32 v[80:81], v[16:17], v[80:81]
	v_pk_mul_f32 v[78:79], v[14:15], v[78:79]
	v_pk_mul_f32 v[76:77], v[12:13], v[76:77]
	v_pk_mul_f32 v[74:75], v[10:11], v[74:75]
	v_pk_mul_f32 v[88:89], v[6:7], v[88:89]
	v_pk_mul_f32 v[84:85], v[8:9], v[84:85]
	v_lshl_add_u64 v[106:107], v[106:107], 0, v[30:31]
	v_pk_mul_f32 v[96:97], v[96:97], v[110:111]
	v_pk_mul_f32 v[98:99], v[90:91], v[102:103]
	v_pk_mul_f32 v[94:95], v[94:95], v[104:105]
	v_cvt_pk_bf16_f32 v90, v96, v97
	v_cvt_pk_bf16_f32 v91, v92, v93
	v_pk_mul_f32 v[78:79], v[72:73], v[78:79] op_sel_hi:[0,1]
	v_cvt_pk_bf16_f32 v92, v94, v95
	v_cvt_pk_bf16_f32 v93, v98, v99
	v_pk_mul_f32 v[80:81], v[72:73], v[80:81] op_sel_hi:[0,1]
	v_pk_mul_f32 v[74:75], v[72:73], v[74:75] op_sel_hi:[0,1]
	v_pk_mul_f32 v[76:77], v[72:73], v[76:77] op_sel_hi:[0,1]
	v_pk_mul_f32 v[84:85], v[72:73], v[84:85] op_sel_hi:[0,1]
	v_pk_mul_f32 v[88:89], v[72:73], v[88:89] op_sel_hi:[0,1]
	global_store_dwordx4 v[106:107], v[90:93], off sc1
	v_pk_mul_f32 v[94:95], v[78:79], s[26:27] op_sel_hi:[1,0]
	v_pk_mul_f32 v[78:79], v[78:79], v[88:89]
	v_pk_mul_f32 v[92:93], v[80:81], s[26:27] op_sel_hi:[1,0]
	v_pk_mul_f32 v[80:81], v[80:81], v[84:85]
	v_pk_mul_f32 v[84:85], v[76:77], s[26:27] op_sel_hi:[1,0]
	v_pk_mul_f32 v[88:89], v[74:75], s[26:27] op_sel_hi:[1,0]
	v_exp_f32_e32 v94, v94
	v_exp_f32_e32 v92, v92
	v_exp_f32_e32 v93, v93
	v_exp_f32_e32 v95, v95
	v_exp_f32_e32 v88, v88
	v_exp_f32_e32 v84, v84
	v_exp_f32_e32 v85, v85
	v_exp_f32_e32 v89, v89
	v_pk_add_f32 v[92:93], v[92:93], 1.0 op_sel_hi:[1,0]
	v_pk_add_f32 v[94:95], v[94:95], 1.0 op_sel_hi:[1,0]
	v_pk_add_f32 v[84:85], v[84:85], 1.0 op_sel_hi:[1,0]
	v_pk_add_f32 v[88:89], v[88:89], 1.0 op_sel_hi:[1,0]
	v_rcp_f32_e32 v94, v94
	v_rcp_f32_e32 v95, v95
	v_rcp_f32_e32 v92, v92
	v_rcp_f32_e32 v93, v93
	v_rcp_f32_e32 v88, v88
	v_rcp_f32_e32 v84, v84
	v_rcp_f32_e32 v85, v85
	v_rcp_f32_e32 v89, v89
	v_pk_mul_f32 v[86:87], v[2:3], v[86:87]
	v_pk_mul_f32 v[82:83], v[4:5], v[82:83]
	v_add_u32_e32 v90, 0x80, v158
	v_pk_mul_f32 v[82:83], v[72:73], v[82:83] op_sel_hi:[0,1]
	v_pk_mul_f32 v[86:87], v[72:73], v[86:87] op_sel_hi:[0,1]
	v_mad_i64_i32 v[90:91], s[0:1], v90, s52, v[28:29]
	v_pk_mul_f32 v[74:75], v[74:75], v[86:87]
	v_pk_mul_f32 v[76:77], v[76:77], v[82:83]
	v_lshl_add_u64 v[90:91], v[90:91], 0, v[30:31]
	v_pk_mul_f32 v[80:81], v[80:81], v[92:93]
	v_pk_mul_f32 v[78:79], v[78:79], v[94:95]
	v_pk_mul_f32 v[82:83], v[76:77], v[84:85]
	v_pk_mul_f32 v[76:77], v[74:75], v[88:89]
	v_cvt_pk_bf16_f32 v74, v78, v79
	v_cvt_pk_bf16_f32 v75, v80, v81
	v_add_u32_e32 v72, 0x90, v158
	v_cvt_pk_bf16_f32 v76, v76, v77
	v_cvt_pk_bf16_f32 v77, v82, v83
	global_store_dwordx4 v[90:91], v[74:77], off sc1
	v_pk_mul_f32 v[62:63], v[16:17], v[62:63]
	v_pk_mul_f32 v[60:61], v[14:15], v[60:61]
	v_mad_i64_i32 v[74:75], s[0:1], v72, s52, v[28:29]
	v_mov_b32_e32 v72, v73
	v_pk_mul_f32 v[58:59], v[12:13], v[58:59]
	v_pk_mul_f32 v[56:57], v[10:11], v[56:57]
	v_pk_mul_f32 v[70:71], v[6:7], v[70:71]
	v_pk_mul_f32 v[66:67], v[8:9], v[66:67]
	v_pk_mul_f32 v[60:61], v[72:73], v[60:61] op_sel_hi:[0,1]
	v_pk_mul_f32 v[62:63], v[72:73], v[62:63] op_sel_hi:[0,1]
	v_pk_mul_f32 v[56:57], v[72:73], v[56:57] op_sel_hi:[0,1]
	v_pk_mul_f32 v[58:59], v[72:73], v[58:59] op_sel_hi:[0,1]
	v_pk_mul_f32 v[66:67], v[72:73], v[66:67] op_sel_hi:[0,1]
	v_pk_mul_f32 v[70:71], v[72:73], v[70:71] op_sel_hi:[0,1]
	v_pk_mul_f32 v[76:77], v[62:63], s[26:27] op_sel_hi:[1,0]
	v_pk_mul_f32 v[78:79], v[60:61], s[26:27] op_sel_hi:[1,0]
	v_pk_mul_f32 v[60:61], v[60:61], v[70:71]
	v_pk_mul_f32 v[62:63], v[62:63], v[66:67]
	v_pk_mul_f32 v[66:67], v[58:59], s[26:27] op_sel_hi:[1,0]
	v_pk_mul_f32 v[70:71], v[56:57], s[26:27] op_sel_hi:[1,0]
	v_exp_f32_e32 v78, v78
	v_exp_f32_e32 v76, v76
	v_exp_f32_e32 v77, v77
	v_exp_f32_e32 v79, v79
	v_exp_f32_e32 v70, v70
	v_exp_f32_e32 v66, v66
	v_exp_f32_e32 v67, v67
	v_exp_f32_e32 v71, v71
	v_pk_mul_f32 v[68:69], v[2:3], v[68:69]
	v_pk_mul_f32 v[64:65], v[4:5], v[64:65]
	v_pk_mul_f32 v[68:69], v[72:73], v[68:69] op_sel_hi:[0,1]
	v_pk_mul_f32 v[64:65], v[72:73], v[64:65] op_sel_hi:[0,1]
	v_pk_add_f32 v[72:73], v[76:77], 1.0 op_sel_hi:[1,0]
	v_pk_add_f32 v[76:77], v[78:79], 1.0 op_sel_hi:[1,0]
	v_pk_add_f32 v[66:67], v[66:67], 1.0 op_sel_hi:[1,0]
	v_pk_add_f32 v[70:71], v[70:71], 1.0 op_sel_hi:[1,0]
	v_cvt_f32_i32_e32 v47, v47
	v_cvt_f32_i32_e32 v46, v46
	v_cvt_f32_i32_e32 v49, v49
	v_cvt_f32_i32_e32 v48, v48
	v_cvt_f32_i32_e32 v43, v43
	v_cvt_f32_i32_e32 v42, v42
	v_cvt_f32_i32_e32 v45, v45
	v_cvt_f32_i32_e32 v44, v44
	v_rcp_f32_e32 v76, v76
	v_rcp_f32_e32 v77, v77
	v_rcp_f32_e32 v70, v70
	v_rcp_f32_e32 v66, v66
	v_rcp_f32_e32 v67, v67
	v_rcp_f32_e32 v71, v71
	v_rcp_f32_e32 v72, v72
	v_rcp_f32_e32 v73, v73
	v_cvt_f32_i32_e32 v39, v39
	v_cvt_f32_i32_e32 v38, v38
	v_cvt_f32_i32_e32 v41, v41
	v_cvt_f32_i32_e32 v40, v40
	v_cvt_f32_i32_e32 v35, v35
	v_cvt_f32_i32_e32 v34, v34
	v_cvt_f32_i32_e32 v37, v37
	v_cvt_f32_i32_e32 v36, v36
	v_pk_mul_f32 v[56:57], v[56:57], v[68:69]
	v_pk_mul_f32 v[58:59], v[58:59], v[64:65]
	v_lshl_add_u64 v[74:75], v[74:75], 0, v[30:31]
	v_pk_mul_f32 v[60:61], v[60:61], v[76:77]
	v_pk_mul_f32 v[64:65], v[58:59], v[66:67]
	v_pk_mul_f32 v[58:59], v[56:57], v[70:71]
	v_cvt_pk_bf16_f32 v56, v60, v61
	v_pk_mul_f32 v[48:49], v[16:17], v[48:49]
	v_pk_mul_f32 v[46:47], v[14:15], v[46:47]
	v_pk_mul_f32 v[44:45], v[12:13], v[44:45]
	v_pk_mul_f32 v[42:43], v[10:11], v[42:43]
	v_pk_mul_f32 v[54:55], v[6:7], v[54:55]
	v_pk_mul_f32 v[50:51], v[8:9], v[50:51]
	v_pk_mul_f32 v[52:53], v[2:3], v[52:53]
	v_pk_mul_f32 v[32:33], v[4:5], v[32:33]
	v_pk_mul_f32 v[62:63], v[62:63], v[72:73]
	v_pk_mul_f32 v[46:47], v[26:27], v[46:47] op_sel_hi:[0,1]
	v_cvt_pk_bf16_f32 v57, v62, v63
	v_cvt_pk_bf16_f32 v58, v58, v59
	v_cvt_pk_bf16_f32 v59, v64, v65
	global_store_dwordx4 v[74:75], v[56:59], off sc1
	v_pk_mul_f32 v[48:49], v[26:27], v[48:49] op_sel_hi:[0,1]
	v_pk_mul_f32 v[42:43], v[26:27], v[42:43] op_sel_hi:[0,1]
	v_add_u32_e32 v56, 0xa0, v158
	v_pk_mul_f32 v[44:45], v[26:27], v[44:45] op_sel_hi:[0,1]
	v_pk_mul_f32 v[50:51], v[26:27], v[50:51] op_sel_hi:[0,1]
	v_pk_mul_f32 v[54:55], v[26:27], v[54:55] op_sel_hi:[0,1]
	v_pk_mul_f32 v[32:33], v[26:27], v[32:33] op_sel_hi:[0,1]
	v_pk_mul_f32 v[52:53], v[26:27], v[52:53] op_sel_hi:[0,1]
	v_add_u32_e32 v26, 0xb0, v158
	v_mad_i64_i32 v[56:57], s[0:1], v56, s52, v[28:29]
	v_mad_i64_i32 v[28:29], s[0:1], v26, s52, v[28:29]
	v_pk_mul_f32 v[16:17], v[16:17], v[40:41]
	v_pk_mul_f32 v[14:15], v[14:15], v[38:39]
	v_mov_b32_e32 v26, v27
	v_pk_mul_f32 v[12:13], v[12:13], v[36:37]
	v_pk_mul_f32 v[10:11], v[10:11], v[34:35]
	v_pk_mul_f32 v[6:7], v[6:7], v[24:25]
	v_pk_mul_f32 v[8:9], v[8:9], v[20:21]
	v_pk_mul_f32 v[14:15], v[26:27], v[14:15] op_sel_hi:[0,1]
	v_pk_mul_f32 v[16:17], v[26:27], v[16:17] op_sel_hi:[0,1]
	v_pk_mul_f32 v[10:11], v[26:27], v[10:11] op_sel_hi:[0,1]
	v_pk_mul_f32 v[12:13], v[26:27], v[12:13] op_sel_hi:[0,1]
	v_pk_mul_f32 v[8:9], v[26:27], v[8:9] op_sel_hi:[0,1]
	v_pk_mul_f32 v[6:7], v[26:27], v[6:7] op_sel_hi:[0,1]
	v_pk_mul_f32 v[60:61], v[46:47], s[26:27] op_sel_hi:[1,0]
	v_pk_mul_f32 v[46:47], v[46:47], v[54:55]
	v_pk_mul_f32 v[54:55], v[42:43], s[26:27] op_sel_hi:[1,0]
	v_pk_mul_f32 v[4:5], v[4:5], v[18:19]
	v_pk_mul_f32 v[18:19], v[16:17], s[26:27] op_sel_hi:[1,0]
	v_pk_mul_f32 v[20:21], v[14:15], s[26:27] op_sel_hi:[1,0]
	v_pk_mul_f32 v[6:7], v[14:15], v[6:7]
	v_pk_mul_f32 v[8:9], v[16:17], v[8:9]
	v_pk_mul_f32 v[14:15], v[12:13], s[26:27] op_sel_hi:[1,0]
	v_pk_mul_f32 v[16:17], v[10:11], s[26:27] op_sel_hi:[1,0]
	v_pk_mul_f32 v[58:59], v[48:49], s[26:27] op_sel_hi:[1,0]
	v_pk_mul_f32 v[48:49], v[48:49], v[50:51]
	v_pk_mul_f32 v[50:51], v[44:45], s[26:27] op_sel_hi:[1,0]
	v_exp_f32_e32 v54, v54
	v_exp_f32_e32 v55, v55
	v_exp_f32_e32 v16, v16
	v_exp_f32_e32 v14, v14
	v_exp_f32_e32 v15, v15
	v_exp_f32_e32 v17, v17
	v_exp_f32_e32 v60, v60
	v_exp_f32_e32 v58, v58
	v_exp_f32_e32 v59, v59
	v_exp_f32_e32 v61, v61
	v_exp_f32_e32 v50, v50
	v_exp_f32_e32 v51, v51
	v_exp_f32_e32 v20, v20
	v_exp_f32_e32 v18, v18
	v_exp_f32_e32 v19, v19
	v_exp_f32_e32 v21, v21
	v_pk_add_f32 v[54:55], v[54:55], 1.0 op_sel_hi:[1,0]
	v_pk_add_f32 v[14:15], v[14:15], 1.0 op_sel_hi:[1,0]
	v_pk_add_f32 v[16:17], v[16:17], 1.0 op_sel_hi:[1,0]
	v_pk_add_f32 v[58:59], v[58:59], 1.0 op_sel_hi:[1,0]
	v_pk_add_f32 v[60:61], v[60:61], 1.0 op_sel_hi:[1,0]
	v_pk_add_f32 v[50:51], v[50:51], 1.0 op_sel_hi:[1,0]
	v_rcp_f32_e32 v54, v54
	v_rcp_f32_e32 v55, v55
	v_pk_add_f32 v[18:19], v[18:19], 1.0 op_sel_hi:[1,0]
	v_pk_add_f32 v[20:21], v[20:21], 1.0 op_sel_hi:[1,0]
	v_rcp_f32_e32 v16, v16
	v_rcp_f32_e32 v14, v14
	v_rcp_f32_e32 v15, v15
	v_rcp_f32_e32 v17, v17
	v_rcp_f32_e32 v60, v60
	v_rcp_f32_e32 v61, v61
	v_rcp_f32_e32 v58, v58
	v_rcp_f32_e32 v59, v59
	v_rcp_f32_e32 v50, v50
	v_rcp_f32_e32 v51, v51
	v_pk_mul_f32 v[2:3], v[2:3], v[22:23]
	v_rcp_f32_e32 v20, v20
	v_rcp_f32_e32 v21, v21
	v_rcp_f32_e32 v18, v18
	v_rcp_f32_e32 v19, v19
	v_pk_mul_f32 v[4:5], v[26:27], v[4:5] op_sel_hi:[0,1]
	v_pk_mul_f32 v[2:3], v[26:27], v[2:3] op_sel_hi:[0,1]
	v_pk_mul_f32 v[42:43], v[42:43], v[52:53]
	v_pk_mul_f32 v[2:3], v[10:11], v[2:3]
	v_pk_mul_f32 v[4:5], v[12:13], v[4:5]
	v_lshl_add_u64 v[56:57], v[56:57], 0, v[30:31]
	v_pk_mul_f32 v[32:33], v[44:45], v[32:33]
	v_pk_mul_f32 v[44:45], v[42:43], v[54:55]
	v_lshl_add_u64 v[28:29], v[28:29], 0, v[30:31]
	v_pk_mul_f32 v[10:11], v[4:5], v[14:15]
	v_pk_mul_f32 v[4:5], v[2:3], v[16:17]
	s_andn2_b64 vcc, exec, s[4:5]
	s_mov_b64 s[0:1], -1
	v_pk_mul_f32 v[48:49], v[48:49], v[58:59]
	v_pk_mul_f32 v[46:47], v[46:47], v[60:61]
	v_pk_mul_f32 v[32:33], v[32:33], v[50:51]
	v_cvt_pk_bf16_f32 v42, v46, v47
	v_cvt_pk_bf16_f32 v43, v48, v49
	v_cvt_pk_bf16_f32 v44, v44, v45
	v_pk_mul_f32 v[8:9], v[8:9], v[18:19]
	v_cvt_pk_bf16_f32 v45, v32, v33
	global_store_dwordx4 v[56:57], v[42:45], off sc1
	v_pk_mul_f32 v[6:7], v[6:7], v[20:21]
	s_nop 0
	v_cvt_pk_bf16_f32 v2, v6, v7
	v_cvt_pk_bf16_f32 v3, v8, v9
	v_cvt_pk_bf16_f32 v4, v4, v5
	v_cvt_pk_bf16_f32 v5, v10, v11
	global_store_dwordx4 v[28:29], v[2:5], off sc1
	s_cbranch_vccnz .LBB0_349
	s_andn2_b64 vcc, exec, s[6:7]
	s_cbranch_vccnz .LBB0_348
	s_barrier
	s_branch .LBB0_348

.LBB0_1075:
	s_lshl_b32 s1, s33, 2
	s_add_i32 s1, s0, s1
	v_cvt_f32_i32_e32 v166, v96
	v_cvt_f32_i32_e32 v96, v70
	v_cvt_f32_i32_e32 v70, v22
	v_cvt_f32_i32_e32 v22, v2
	v_lshl_add_u32 v2, v148, 2, s1
	s_lshl_b32 s1, s34, 2
	s_add_i32 s0, s0, s1
	v_cvt_f32_i32_e32 v159, v127
	v_cvt_f32_i32_e32 v158, v126
	v_cvt_f32_i32_e32 v161, v129
	v_cvt_f32_i32_e32 v160, v128
	v_cvt_f32_i32_e32 v165, v125
	v_cvt_f32_i32_e32 v164, v124
	v_cvt_f32_i32_e32 v125, v115
	v_cvt_f32_i32_e32 v124, v114
	v_cvt_f32_i32_e32 v171, v93
	v_cvt_f32_i32_e32 v170, v92
	v_cvt_f32_i32_e32 v175, v87
	v_cvt_f32_i32_e32 v174, v86
	v_cvt_f32_i32_e32 v93, v73
	v_cvt_f32_i32_e32 v92, v72
	v_cvt_f32_i32_e32 v87, v27
	v_cvt_f32_i32_e32 v86, v26
	ds_read2_b32 v[176:177], v2 offset1:16
	ds_read2_b32 v[114:115], v2 offset0:32 offset1:48
	ds_read2_b32 v[72:73], v2 offset0:128 offset1:144
	ds_read2_b32 v[26:27], v2 offset0:160 offset1:176
	v_lshl_add_u32 v2, v150, 2, s0
	v_cvt_f32_i32_e32 v163, v123
	v_cvt_f32_i32_e32 v162, v122
	v_cvt_f32_i32_e32 v129, v119
	v_cvt_f32_i32_e32 v128, v118
	v_cvt_f32_i32_e32 v137, v121
	v_cvt_f32_i32_e32 v136, v120
	v_cvt_f32_i32_e32 v127, v117
	v_cvt_f32_i32_e32 v126, v116
	v_cvt_f32_i32_e32 v167, v97
	v_cvt_f32_i32_e32 v169, v95
	v_cvt_f32_i32_e32 v168, v94
	v_cvt_f32_i32_e32 v173, v91
	v_cvt_f32_i32_e32 v172, v90
	v_cvt_f32_i32_e32 v139, v85
	v_cvt_f32_i32_e32 v138, v84
	v_cvt_f32_i32_e32 v119, v81
	v_cvt_f32_i32_e32 v118, v80
	v_cvt_f32_i32_e32 v123, v79
	v_cvt_f32_i32_e32 v122, v78
	v_cvt_f32_i32_e32 v117, v77
	v_cvt_f32_i32_e32 v116, v76
	v_cvt_f32_i32_e32 v121, v75
	v_cvt_f32_i32_e32 v120, v74
	v_cvt_f32_i32_e32 v97, v71
	v_cvt_f32_i32_e32 v91, v69
	v_cvt_f32_i32_e32 v90, v68
	v_cvt_f32_i32_e32 v95, v67
	v_cvt_f32_i32_e32 v94, v66
	v_cvt_f32_i32_e32 v79, v63
	v_cvt_f32_i32_e32 v78, v62
	v_cvt_f32_i32_e32 v81, v65
	v_cvt_f32_i32_e32 v80, v64
	v_cvt_f32_i32_e32 v75, v59
	v_cvt_f32_i32_e32 v74, v58
	v_cvt_f32_i32_e32 v77, v61
	v_cvt_f32_i32_e32 v76, v60
	v_cvt_f32_i32_e32 v61, v55
	v_cvt_f32_i32_e32 v60, v54
	v_cvt_f32_i32_e32 v63, v57
	v_cvt_f32_i32_e32 v62, v56
	v_cvt_f32_i32_e32 v57, v51
	v_cvt_f32_i32_e32 v56, v50
	v_cvt_f32_i32_e32 v59, v53
	v_cvt_f32_i32_e32 v58, v52
	v_cvt_f32_i32_e32 v85, v33
	v_cvt_f32_i32_e32 v84, v32
	v_cvt_f32_i32_e32 v67, v25
	v_cvt_f32_i32_e32 v66, v24
	v_cvt_f32_i32_e32 v71, v23
	v_cvt_f32_i32_e32 v65, v21
	v_cvt_f32_i32_e32 v64, v20
	v_cvt_f32_i32_e32 v69, v19
	v_cvt_f32_i32_e32 v68, v18
	v_cvt_f32_i32_e32 v51, v17
	v_cvt_f32_i32_e32 v50, v16
	v_cvt_f32_i32_e32 v55, v15
	v_cvt_f32_i32_e32 v54, v14
	v_cvt_f32_i32_e32 v33, v13
	v_cvt_f32_i32_e32 v32, v12
	v_cvt_f32_i32_e32 v53, v11
	v_cvt_f32_i32_e32 v52, v10
	v_cvt_f32_i32_e32 v21, v9
	v_cvt_f32_i32_e32 v20, v8
	v_cvt_f32_i32_e32 v25, v7
	v_cvt_f32_i32_e32 v24, v6
	v_cvt_f32_i32_e32 v19, v5
	v_cvt_f32_i32_e32 v18, v4
	v_cvt_f32_i32_e32 v23, v3
	ds_read_b128 v[14:17], v2 offset:1024
	ds_read_b128 v[10:13], v2 offset:1040
	ds_read_b128 v[6:9], v2 offset:1536
	ds_read_b128 v[2:5], v2 offset:1552
	v_cvt_f32_i32_e32 v140, v88
	s_waitcnt lgkmcnt(0)
	v_pk_mul_f32 v[160:161], v[16:17], v[160:161]
	v_pk_mul_f32 v[158:159], v[14:15], v[158:159]
	v_pk_mul_f32 v[160:161], v[176:177], v[160:161] op_sel_hi:[0,1]
	v_pk_mul_f32 v[158:159], v[176:177], v[158:159] op_sel_hi:[0,1]
	v_pk_mul_f32 v[162:163], v[10:11], v[162:163]
	v_pk_mul_f32 v[168:169], v[6:7], v[168:169]
	v_pk_mul_f32 v[164:165], v[12:13], v[164:165]
	v_pk_mul_f32 v[162:163], v[176:177], v[162:163] op_sel_hi:[0,1]
	v_pk_mul_f32 v[166:167], v[8:9], v[166:167]
	v_pk_mul_f32 v[168:169], v[176:177], v[168:169] op_sel_hi:[0,1]
	v_pk_mul_f32 v[180:181], v[160:161], s[22:23] op_sel_hi:[1,0]
	v_pk_mul_f32 v[182:183], v[158:159], s[22:23] op_sel_hi:[1,0]
	v_pk_mul_f32 v[164:165], v[176:177], v[164:165] op_sel_hi:[0,1]
	v_pk_mul_f32 v[166:167], v[176:177], v[166:167] op_sel_hi:[0,1]
	v_exp_f32_e32 v182, v182
	v_exp_f32_e32 v180, v180
	v_exp_f32_e32 v181, v181
	v_exp_f32_e32 v183, v183
	v_pk_mul_f32 v[158:159], v[158:159], v[168:169]
	v_pk_mul_f32 v[168:169], v[162:163], s[22:23] op_sel_hi:[1,0]
	v_pk_mul_f32 v[160:161], v[160:161], v[166:167]
	v_pk_mul_f32 v[166:167], v[164:165], s[22:23] op_sel_hi:[1,0]
	v_exp_f32_e32 v168, v168
	v_exp_f32_e32 v169, v169
	v_exp_f32_e32 v166, v166
	v_exp_f32_e32 v167, v167
	v_pk_add_f32 v[180:181], v[180:181], 1.0 op_sel_hi:[1,0]
	v_pk_add_f32 v[182:183], v[182:183], 1.0 op_sel_hi:[1,0]
	v_rcp_f32_e32 v180, v180
	v_rcp_f32_e32 v182, v182
	v_rcp_f32_e32 v183, v183
	v_rcp_f32_e32 v181, v181
	v_pk_add_f32 v[168:169], v[168:169], 1.0 op_sel_hi:[1,0]
	v_pk_add_f32 v[166:167], v[166:167], 1.0 op_sel_hi:[1,0]
	v_rcp_f32_e32 v168, v168
	v_rcp_f32_e32 v169, v169
	v_cvt_f32_i32_e32 v88, v30
	v_lshl_or_b32 v30, s52, 7, v151
	v_pk_mul_f32 v[172:173], v[2:3], v[172:173]
	v_rcp_f32_e32 v166, v166
	v_rcp_f32_e32 v167, v167
	v_cvt_f32_i32_e32 v141, v89
	v_cvt_f32_i32_e32 v143, v83
	v_cvt_f32_i32_e32 v142, v82
	v_cvt_f32_i32_e32 v89, v31
	v_cvt_f32_i32_e32 v83, v29
	v_cvt_f32_i32_e32 v82, v28
	v_lshl_add_u32 v157, s53, 8, v149
	v_ashrrev_i32_e32 v31, 31, v30
	v_mov_b64_e32 v[28:29], s[16:17]
	v_pk_mul_f32 v[170:171], v[4:5], v[170:171]
	v_pk_mul_f32 v[172:173], v[176:177], v[172:173] op_sel_hi:[0,1]
	v_mad_i64_i32 v[178:179], s[0:1], v157, s46, v[28:29]
	v_lshlrev_b64 v[30:31], 1, v[30:31]
	v_pk_mul_f32 v[170:171], v[176:177], v[170:171] op_sel_hi:[0,1]
	v_pk_mul_f32 v[160:161], v[160:161], v[180:181]
	v_pk_mul_f32 v[158:159], v[158:159], v[182:183]
	v_pk_mul_f32 v[162:163], v[162:163], v[172:173]
	v_lshl_add_u64 v[178:179], v[178:179], 0, v[30:31]
	v_pk_mul_f32 v[164:165], v[164:165], v[170:171]
	v_pk_mul_f32 v[162:163], v[162:163], v[168:169]
	v_cvt_pk_bf16_f32 v158, v158, v159
	v_cvt_pk_bf16_f32 v159, v160, v161
	v_pk_mul_f32 v[164:165], v[164:165], v[166:167]
	v_cvt_pk_bf16_f32 v160, v162, v163
	v_pk_mul_f32 v[136:137], v[16:17], v[136:137]
	v_cvt_pk_bf16_f32 v161, v164, v165
	global_store_dwordx4 v[178:179], v[158:161], off sc1
	v_pk_mul_f32 v[128:129], v[14:15], v[128:129]
	v_pk_mul_f32 v[126:127], v[12:13], v[126:127]
	v_mov_b32_e32 v160, v177
	v_pk_mul_f32 v[136:137], v[160:161], v[136:137] op_sel_hi:[0,1]
	v_pk_mul_f32 v[164:165], v[136:137], s[22:23] op_sel_hi:[1,0]
	v_pk_mul_f32 v[124:125], v[10:11], v[124:125]
	v_exp_f32_e32 v164, v164
	v_exp_f32_e32 v165, v165
	v_pk_mul_f32 v[162:163], v[6:7], v[174:175]
	v_pk_mul_f32 v[140:141], v[8:9], v[140:141]
	v_pk_mul_f32 v[128:129], v[160:161], v[128:129] op_sel_hi:[0,1]
	v_pk_mul_f32 v[124:125], v[160:161], v[124:125] op_sel_hi:[0,1]
	v_pk_mul_f32 v[126:127], v[160:161], v[126:127] op_sel_hi:[0,1]
	v_pk_mul_f32 v[140:141], v[160:161], v[140:141] op_sel_hi:[0,1]
	v_pk_mul_f32 v[162:163], v[160:161], v[162:163] op_sel_hi:[0,1]
	v_pk_mul_f32 v[142:143], v[2:3], v[142:143]
	v_pk_mul_f32 v[138:139], v[4:5], v[138:139]
	v_pk_mul_f32 v[166:167], v[128:129], s[22:23] op_sel_hi:[1,0]
	v_pk_mul_f32 v[138:139], v[160:161], v[138:139] op_sel_hi:[0,1]
	v_pk_mul_f32 v[142:143], v[160:161], v[142:143] op_sel_hi:[0,1]
	v_pk_add_f32 v[160:161], v[164:165], 1.0 op_sel_hi:[1,0]
	v_pk_mul_f32 v[128:129], v[128:129], v[162:163]
	v_pk_mul_f32 v[136:137], v[136:137], v[140:141]
	v_pk_mul_f32 v[140:141], v[126:127], s[22:23] op_sel_hi:[1,0]
	v_pk_mul_f32 v[162:163], v[124:125], s[22:23] op_sel_hi:[1,0]
	v_rcp_f32_e32 v160, v160
	v_rcp_f32_e32 v161, v161
	v_exp_f32_e32 v162, v162
	v_exp_f32_e32 v140, v140
	v_exp_f32_e32 v141, v141
	v_exp_f32_e32 v163, v163
	v_exp_f32_e32 v166, v166
	v_exp_f32_e32 v167, v167
	v_pk_mul_f32 v[136:137], v[136:137], v[160:161]
	v_pk_add_f32 v[140:141], v[140:141], 1.0 op_sel_hi:[1,0]
	v_pk_add_f32 v[160:161], v[162:163], 1.0 op_sel_hi:[1,0]
	v_cvt_f32_i32_e32 v111, v111
	v_cvt_f32_i32_e32 v110, v110
	v_cvt_f32_i32_e32 v113, v113
	v_cvt_f32_i32_e32 v112, v112
	v_cvt_f32_i32_e32 v107, v107
	v_cvt_f32_i32_e32 v106, v106
	v_cvt_f32_i32_e32 v109, v109
	v_cvt_f32_i32_e32 v108, v108
	v_pk_add_f32 v[164:165], v[166:167], 1.0 op_sel_hi:[1,0]
	v_rcp_f32_e32 v160, v160
	v_rcp_f32_e32 v140, v140
	v_rcp_f32_e32 v141, v141
	v_rcp_f32_e32 v161, v161
	v_rcp_f32_e32 v164, v164
	v_rcp_f32_e32 v165, v165
	v_or_b32_e32 v158, 16, v157
	v_pk_mul_f32 v[124:125], v[124:125], v[142:143]
	v_pk_mul_f32 v[126:127], v[126:127], v[138:139]
	v_mad_i64_i32 v[158:159], s[0:1], v158, s46, v[28:29]
	v_pk_mul_f32 v[138:139], v[126:127], v[140:141]
	v_pk_mul_f32 v[126:127], v[124:125], v[160:161]
	v_pk_mul_f32 v[112:113], v[16:17], v[112:113]
	v_pk_mul_f32 v[110:111], v[14:15], v[110:111]
	v_pk_mul_f32 v[108:109], v[12:13], v[108:109]
	v_pk_mul_f32 v[106:107], v[10:11], v[106:107]
	v_pk_mul_f32 v[122:123], v[6:7], v[122:123]
	v_pk_mul_f32 v[118:119], v[8:9], v[118:119]
	v_lshl_add_u64 v[158:159], v[158:159], 0, v[30:31]
	v_pk_mul_f32 v[128:129], v[128:129], v[164:165]
	v_pk_mul_f32 v[110:111], v[114:115], v[110:111] op_sel_hi:[0,1]
	v_cvt_pk_bf16_f32 v124, v128, v129
	v_cvt_pk_bf16_f32 v125, v136, v137
	v_cvt_pk_bf16_f32 v126, v126, v127
	v_cvt_pk_bf16_f32 v127, v138, v139
	v_pk_mul_f32 v[112:113], v[114:115], v[112:113] op_sel_hi:[0,1]
	v_pk_mul_f32 v[106:107], v[114:115], v[106:107] op_sel_hi:[0,1]
	v_pk_mul_f32 v[108:109], v[114:115], v[108:109] op_sel_hi:[0,1]
	v_pk_mul_f32 v[118:119], v[114:115], v[118:119] op_sel_hi:[0,1]
	v_pk_mul_f32 v[122:123], v[114:115], v[122:123] op_sel_hi:[0,1]
	global_store_dwordx4 v[158:159], v[124:127], off sc1
	v_pk_mul_f32 v[128:129], v[110:111], s[22:23] op_sel_hi:[1,0]
	v_pk_mul_f32 v[110:111], v[110:111], v[122:123]
	v_pk_mul_f32 v[126:127], v[112:113], s[22:23] op_sel_hi:[1,0]
	v_pk_mul_f32 v[112:113], v[112:113], v[118:119]
	v_pk_mul_f32 v[118:119], v[108:109], s[22:23] op_sel_hi:[1,0]
	v_pk_mul_f32 v[122:123], v[106:107], s[22:23] op_sel_hi:[1,0]
	v_exp_f32_e32 v118, v118
	v_exp_f32_e32 v122, v122
	v_exp_f32_e32 v119, v119
	v_exp_f32_e32 v123, v123
	v_exp_f32_e32 v128, v128
	v_exp_f32_e32 v126, v126
	v_exp_f32_e32 v127, v127
	v_exp_f32_e32 v129, v129
	v_pk_add_f32 v[118:119], v[118:119], 1.0 op_sel_hi:[1,0]
	v_pk_add_f32 v[122:123], v[122:123], 1.0 op_sel_hi:[1,0]
	v_pk_add_f32 v[126:127], v[126:127], 1.0 op_sel_hi:[1,0]
	v_pk_add_f32 v[128:129], v[128:129], 1.0 op_sel_hi:[1,0]
	v_rcp_f32_e32 v122, v122
	v_rcp_f32_e32 v118, v118
	v_rcp_f32_e32 v119, v119
	v_rcp_f32_e32 v123, v123
	v_pk_mul_f32 v[120:121], v[2:3], v[120:121]
	v_pk_mul_f32 v[116:117], v[4:5], v[116:117]
	v_rcp_f32_e32 v128, v128
	v_rcp_f32_e32 v129, v129
	v_rcp_f32_e32 v126, v126
	v_rcp_f32_e32 v127, v127
	v_cvt_f32_i32_e32 v105, v105
	v_cvt_f32_i32_e32 v104, v104
	v_pk_mul_f32 v[116:117], v[114:115], v[116:117] op_sel_hi:[0,1]
	v_pk_mul_f32 v[120:121], v[114:115], v[120:121] op_sel_hi:[0,1]
	v_cvt_f32_i32_e32 v103, v103
	v_cvt_f32_i32_e32 v102, v102
	v_cvt_f32_i32_e32 v99, v99
	v_cvt_f32_i32_e32 v98, v98
	v_cvt_f32_i32_e32 v101, v101
	v_cvt_f32_i32_e32 v100, v100
	v_or_b32_e32 v124, 32, v157
	v_pk_mul_f32 v[106:107], v[106:107], v[120:121]
	v_pk_mul_f32 v[108:109], v[108:109], v[116:117]
	v_mad_i64_i32 v[124:125], s[0:1], v124, s46, v[28:29]
	v_pk_mul_f32 v[116:117], v[108:109], v[118:119]
	v_pk_mul_f32 v[108:109], v[106:107], v[122:123]
	v_lshl_add_u64 v[124:125], v[124:125], 0, v[30:31]
	v_pk_mul_f32 v[112:113], v[112:113], v[126:127]
	v_pk_mul_f32 v[110:111], v[110:111], v[128:129]
	v_pk_mul_f32 v[104:105], v[16:17], v[104:105]
	v_cvt_pk_bf16_f32 v106, v110, v111
	v_cvt_pk_bf16_f32 v107, v112, v113
	v_cvt_pk_bf16_f32 v108, v108, v109
	v_cvt_pk_bf16_f32 v109, v116, v117
	global_store_dwordx4 v[124:125], v[106:109], off sc1
	v_pk_mul_f32 v[102:103], v[14:15], v[102:103]
	v_pk_mul_f32 v[100:101], v[12:13], v[100:101]
	v_mov_b32_e32 v108, v115
	v_pk_mul_f32 v[104:105], v[108:109], v[104:105] op_sel_hi:[0,1]
	v_pk_mul_f32 v[98:99], v[10:11], v[98:99]
	v_pk_mul_f32 v[96:97], v[6:7], v[96:97]
	v_pk_mul_f32 v[92:93], v[8:9], v[92:93]
	v_pk_mul_f32 v[102:103], v[108:109], v[102:103] op_sel_hi:[0,1]
	v_pk_mul_f32 v[98:99], v[108:109], v[98:99] op_sel_hi:[0,1]
	v_pk_mul_f32 v[100:101], v[108:109], v[100:101] op_sel_hi:[0,1]
	v_pk_mul_f32 v[92:93], v[108:109], v[92:93] op_sel_hi:[0,1]
	v_pk_mul_f32 v[96:97], v[108:109], v[96:97] op_sel_hi:[0,1]
	v_pk_mul_f32 v[110:111], v[104:105], s[22:23] op_sel_hi:[1,0]
	v_pk_mul_f32 v[112:113], v[102:103], s[22:23] op_sel_hi:[1,0]
	v_exp_f32_e32 v110, v110
	v_exp_f32_e32 v111, v111
	v_pk_mul_f32 v[96:97], v[102:103], v[96:97]
	v_pk_mul_f32 v[92:93], v[104:105], v[92:93]
	v_pk_mul_f32 v[102:103], v[100:101], s[22:23] op_sel_hi:[1,0]
	v_pk_mul_f32 v[104:105], v[98:99], s[22:23] op_sel_hi:[1,0]
	v_exp_f32_e32 v112, v112
	v_exp_f32_e32 v113, v113
	v_exp_f32_e32 v104, v104
	v_exp_f32_e32 v102, v102
	v_exp_f32_e32 v103, v103
	v_exp_f32_e32 v105, v105
	v_pk_mul_f32 v[94:95], v[2:3], v[94:95]
	v_pk_mul_f32 v[90:91], v[4:5], v[90:91]
	v_pk_mul_f32 v[94:95], v[108:109], v[94:95] op_sel_hi:[0,1]
	v_pk_mul_f32 v[90:91], v[108:109], v[90:91] op_sel_hi:[0,1]
	v_pk_add_f32 v[108:109], v[110:111], 1.0 op_sel_hi:[1,0]
	v_pk_add_f32 v[110:111], v[112:113], 1.0 op_sel_hi:[1,0]
	v_rcp_f32_e32 v108, v108
	v_rcp_f32_e32 v109, v109
	v_pk_add_f32 v[102:103], v[102:103], 1.0 op_sel_hi:[1,0]
	v_pk_add_f32 v[104:105], v[104:105], 1.0 op_sel_hi:[1,0]
	v_rcp_f32_e32 v110, v110
	v_rcp_f32_e32 v111, v111
	v_rcp_f32_e32 v104, v104
	v_rcp_f32_e32 v102, v102
	v_rcp_f32_e32 v103, v103
	v_rcp_f32_e32 v105, v105
	v_or_b32_e32 v106, 48, v157
	v_mad_i64_i32 v[106:107], s[0:1], v106, s46, v[28:29]
	v_pk_mul_f32 v[92:93], v[92:93], v[108:109]
	v_pk_mul_f32 v[94:95], v[98:99], v[94:95]
	v_pk_mul_f32 v[90:91], v[100:101], v[90:91]
	v_pk_mul_f32 v[80:81], v[16:17], v[80:81]
	v_pk_mul_f32 v[78:79], v[14:15], v[78:79]
	v_pk_mul_f32 v[76:77], v[12:13], v[76:77]
	v_pk_mul_f32 v[74:75], v[10:11], v[74:75]
	v_pk_mul_f32 v[88:89], v[6:7], v[88:89]
	v_pk_mul_f32 v[84:85], v[8:9], v[84:85]
	v_lshl_add_u64 v[106:107], v[106:107], 0, v[30:31]
	v_pk_mul_f32 v[96:97], v[96:97], v[110:111]
	v_pk_mul_f32 v[98:99], v[90:91], v[102:103]
	v_pk_mul_f32 v[94:95], v[94:95], v[104:105]
	v_cvt_pk_bf16_f32 v90, v96, v97
	v_cvt_pk_bf16_f32 v91, v92, v93
	v_pk_mul_f32 v[78:79], v[72:73], v[78:79] op_sel_hi:[0,1]
	v_cvt_pk_bf16_f32 v92, v94, v95
	v_cvt_pk_bf16_f32 v93, v98, v99
	v_pk_mul_f32 v[80:81], v[72:73], v[80:81] op_sel_hi:[0,1]
	v_pk_mul_f32 v[74:75], v[72:73], v[74:75] op_sel_hi:[0,1]
	v_pk_mul_f32 v[76:77], v[72:73], v[76:77] op_sel_hi:[0,1]
	v_pk_mul_f32 v[84:85], v[72:73], v[84:85] op_sel_hi:[0,1]
	v_pk_mul_f32 v[88:89], v[72:73], v[88:89] op_sel_hi:[0,1]
	global_store_dwordx4 v[106:107], v[90:93], off sc1
	v_pk_mul_f32 v[94:95], v[78:79], s[22:23] op_sel_hi:[1,0]
	v_pk_mul_f32 v[78:79], v[78:79], v[88:89]
	v_pk_mul_f32 v[92:93], v[80:81], s[22:23] op_sel_hi:[1,0]
	v_pk_mul_f32 v[80:81], v[80:81], v[84:85]
	v_pk_mul_f32 v[84:85], v[76:77], s[22:23] op_sel_hi:[1,0]
	v_pk_mul_f32 v[88:89], v[74:75], s[22:23] op_sel_hi:[1,0]
	v_exp_f32_e32 v94, v94
	v_exp_f32_e32 v92, v92
	v_exp_f32_e32 v93, v93
	v_exp_f32_e32 v95, v95
	v_exp_f32_e32 v88, v88
	v_exp_f32_e32 v84, v84
	v_exp_f32_e32 v85, v85
	v_exp_f32_e32 v89, v89
	v_pk_add_f32 v[92:93], v[92:93], 1.0 op_sel_hi:[1,0]
	v_pk_add_f32 v[94:95], v[94:95], 1.0 op_sel_hi:[1,0]
	v_pk_add_f32 v[84:85], v[84:85], 1.0 op_sel_hi:[1,0]
	v_pk_add_f32 v[88:89], v[88:89], 1.0 op_sel_hi:[1,0]
	v_rcp_f32_e32 v94, v94
	v_rcp_f32_e32 v95, v95
	v_rcp_f32_e32 v92, v92
	v_rcp_f32_e32 v93, v93
	v_rcp_f32_e32 v88, v88
	v_rcp_f32_e32 v84, v84
	v_rcp_f32_e32 v85, v85
	v_rcp_f32_e32 v89, v89
	v_pk_mul_f32 v[86:87], v[2:3], v[86:87]
	v_pk_mul_f32 v[82:83], v[4:5], v[82:83]
	v_add_u32_e32 v90, 0x80, v157
	v_pk_mul_f32 v[82:83], v[72:73], v[82:83] op_sel_hi:[0,1]
	v_pk_mul_f32 v[86:87], v[72:73], v[86:87] op_sel_hi:[0,1]
	v_mad_i64_i32 v[90:91], s[0:1], v90, s46, v[28:29]
	v_pk_mul_f32 v[74:75], v[74:75], v[86:87]
	v_pk_mul_f32 v[76:77], v[76:77], v[82:83]
	v_lshl_add_u64 v[90:91], v[90:91], 0, v[30:31]
	v_pk_mul_f32 v[80:81], v[80:81], v[92:93]
	v_pk_mul_f32 v[78:79], v[78:79], v[94:95]
	v_pk_mul_f32 v[82:83], v[76:77], v[84:85]
	v_pk_mul_f32 v[76:77], v[74:75], v[88:89]
	v_cvt_pk_bf16_f32 v74, v78, v79
	v_cvt_pk_bf16_f32 v75, v80, v81
	v_add_u32_e32 v72, 0x90, v157
	v_cvt_pk_bf16_f32 v76, v76, v77
	v_cvt_pk_bf16_f32 v77, v82, v83
	global_store_dwordx4 v[90:91], v[74:77], off sc1
	v_pk_mul_f32 v[62:63], v[16:17], v[62:63]
	v_pk_mul_f32 v[60:61], v[14:15], v[60:61]
	v_mad_i64_i32 v[74:75], s[0:1], v72, s46, v[28:29]
	v_mov_b32_e32 v72, v73
	v_pk_mul_f32 v[58:59], v[12:13], v[58:59]
	v_pk_mul_f32 v[56:57], v[10:11], v[56:57]
	v_pk_mul_f32 v[70:71], v[6:7], v[70:71]
	v_pk_mul_f32 v[66:67], v[8:9], v[66:67]
	v_pk_mul_f32 v[60:61], v[72:73], v[60:61] op_sel_hi:[0,1]
	v_pk_mul_f32 v[62:63], v[72:73], v[62:63] op_sel_hi:[0,1]
	v_pk_mul_f32 v[56:57], v[72:73], v[56:57] op_sel_hi:[0,1]
	v_pk_mul_f32 v[58:59], v[72:73], v[58:59] op_sel_hi:[0,1]
	v_pk_mul_f32 v[66:67], v[72:73], v[66:67] op_sel_hi:[0,1]
	v_pk_mul_f32 v[70:71], v[72:73], v[70:71] op_sel_hi:[0,1]
	v_pk_mul_f32 v[76:77], v[62:63], s[22:23] op_sel_hi:[1,0]
	v_pk_mul_f32 v[78:79], v[60:61], s[22:23] op_sel_hi:[1,0]
	v_pk_mul_f32 v[60:61], v[60:61], v[70:71]
	v_pk_mul_f32 v[62:63], v[62:63], v[66:67]
	v_pk_mul_f32 v[66:67], v[58:59], s[22:23] op_sel_hi:[1,0]
	v_pk_mul_f32 v[70:71], v[56:57], s[22:23] op_sel_hi:[1,0]
	v_exp_f32_e32 v78, v78
	v_exp_f32_e32 v76, v76
	v_exp_f32_e32 v77, v77
	v_exp_f32_e32 v79, v79
	v_exp_f32_e32 v70, v70
	v_exp_f32_e32 v66, v66
	v_exp_f32_e32 v67, v67
	v_exp_f32_e32 v71, v71
	v_pk_mul_f32 v[68:69], v[2:3], v[68:69]
	v_pk_mul_f32 v[64:65], v[4:5], v[64:65]
	v_pk_mul_f32 v[68:69], v[72:73], v[68:69] op_sel_hi:[0,1]
	v_pk_mul_f32 v[64:65], v[72:73], v[64:65] op_sel_hi:[0,1]
	v_pk_add_f32 v[72:73], v[76:77], 1.0 op_sel_hi:[1,0]
	v_pk_add_f32 v[76:77], v[78:79], 1.0 op_sel_hi:[1,0]
	v_pk_add_f32 v[66:67], v[66:67], 1.0 op_sel_hi:[1,0]
	v_pk_add_f32 v[70:71], v[70:71], 1.0 op_sel_hi:[1,0]
	v_cvt_f32_i32_e32 v47, v47
	v_cvt_f32_i32_e32 v46, v46
	v_cvt_f32_i32_e32 v49, v49
	v_cvt_f32_i32_e32 v48, v48
	v_cvt_f32_i32_e32 v43, v43
	v_cvt_f32_i32_e32 v42, v42
	v_cvt_f32_i32_e32 v45, v45
	v_cvt_f32_i32_e32 v44, v44
	v_rcp_f32_e32 v76, v76
	v_rcp_f32_e32 v77, v77
	v_rcp_f32_e32 v70, v70
	v_rcp_f32_e32 v66, v66
	v_rcp_f32_e32 v67, v67
	v_rcp_f32_e32 v71, v71
	v_rcp_f32_e32 v72, v72
	v_rcp_f32_e32 v73, v73
	v_cvt_f32_i32_e32 v39, v39
	v_cvt_f32_i32_e32 v38, v38
	v_cvt_f32_i32_e32 v41, v41
	v_cvt_f32_i32_e32 v40, v40
	v_cvt_f32_i32_e32 v35, v35
	v_cvt_f32_i32_e32 v34, v34
	v_cvt_f32_i32_e32 v37, v37
	v_cvt_f32_i32_e32 v36, v36
	v_pk_mul_f32 v[56:57], v[56:57], v[68:69]
	v_pk_mul_f32 v[58:59], v[58:59], v[64:65]
	v_lshl_add_u64 v[74:75], v[74:75], 0, v[30:31]
	v_pk_mul_f32 v[60:61], v[60:61], v[76:77]
	v_pk_mul_f32 v[64:65], v[58:59], v[66:67]
	v_pk_mul_f32 v[58:59], v[56:57], v[70:71]
	v_cvt_pk_bf16_f32 v56, v60, v61
	v_pk_mul_f32 v[48:49], v[16:17], v[48:49]
	v_pk_mul_f32 v[46:47], v[14:15], v[46:47]
	v_pk_mul_f32 v[44:45], v[12:13], v[44:45]
	v_pk_mul_f32 v[42:43], v[10:11], v[42:43]
	v_pk_mul_f32 v[54:55], v[6:7], v[54:55]
	v_pk_mul_f32 v[50:51], v[8:9], v[50:51]
	v_pk_mul_f32 v[52:53], v[2:3], v[52:53]
	v_pk_mul_f32 v[32:33], v[4:5], v[32:33]
	v_pk_mul_f32 v[62:63], v[62:63], v[72:73]
	v_pk_mul_f32 v[46:47], v[26:27], v[46:47] op_sel_hi:[0,1]
	v_cvt_pk_bf16_f32 v57, v62, v63
	v_cvt_pk_bf16_f32 v58, v58, v59
	v_cvt_pk_bf16_f32 v59, v64, v65
	global_store_dwordx4 v[74:75], v[56:59], off sc1
	v_pk_mul_f32 v[48:49], v[26:27], v[48:49] op_sel_hi:[0,1]
	v_pk_mul_f32 v[42:43], v[26:27], v[42:43] op_sel_hi:[0,1]
	v_add_u32_e32 v56, 0xa0, v157
	v_pk_mul_f32 v[44:45], v[26:27], v[44:45] op_sel_hi:[0,1]
	v_pk_mul_f32 v[50:51], v[26:27], v[50:51] op_sel_hi:[0,1]
	v_pk_mul_f32 v[54:55], v[26:27], v[54:55] op_sel_hi:[0,1]
	v_pk_mul_f32 v[32:33], v[26:27], v[32:33] op_sel_hi:[0,1]
	v_pk_mul_f32 v[52:53], v[26:27], v[52:53] op_sel_hi:[0,1]
	v_add_u32_e32 v26, 0xb0, v157
	v_mad_i64_i32 v[56:57], s[0:1], v56, s46, v[28:29]
	v_mad_i64_i32 v[28:29], s[0:1], v26, s46, v[28:29]
	v_pk_mul_f32 v[16:17], v[16:17], v[40:41]
	v_pk_mul_f32 v[14:15], v[14:15], v[38:39]
	v_mov_b32_e32 v26, v27
	v_pk_mul_f32 v[12:13], v[12:13], v[36:37]
	v_pk_mul_f32 v[10:11], v[10:11], v[34:35]
	v_pk_mul_f32 v[6:7], v[6:7], v[24:25]
	v_pk_mul_f32 v[8:9], v[8:9], v[20:21]
	v_pk_mul_f32 v[14:15], v[26:27], v[14:15] op_sel_hi:[0,1]
	v_pk_mul_f32 v[16:17], v[26:27], v[16:17] op_sel_hi:[0,1]
	v_pk_mul_f32 v[10:11], v[26:27], v[10:11] op_sel_hi:[0,1]
	v_pk_mul_f32 v[12:13], v[26:27], v[12:13] op_sel_hi:[0,1]
	v_pk_mul_f32 v[8:9], v[26:27], v[8:9] op_sel_hi:[0,1]
	v_pk_mul_f32 v[6:7], v[26:27], v[6:7] op_sel_hi:[0,1]
	v_pk_mul_f32 v[60:61], v[46:47], s[22:23] op_sel_hi:[1,0]
	v_pk_mul_f32 v[46:47], v[46:47], v[54:55]
	v_pk_mul_f32 v[54:55], v[42:43], s[22:23] op_sel_hi:[1,0]
	v_pk_mul_f32 v[4:5], v[4:5], v[18:19]
	v_pk_mul_f32 v[18:19], v[16:17], s[22:23] op_sel_hi:[1,0]
	v_pk_mul_f32 v[20:21], v[14:15], s[22:23] op_sel_hi:[1,0]
	v_pk_mul_f32 v[6:7], v[14:15], v[6:7]
	v_pk_mul_f32 v[8:9], v[16:17], v[8:9]
	v_pk_mul_f32 v[14:15], v[12:13], s[22:23] op_sel_hi:[1,0]
	v_pk_mul_f32 v[16:17], v[10:11], s[22:23] op_sel_hi:[1,0]
	v_pk_mul_f32 v[58:59], v[48:49], s[22:23] op_sel_hi:[1,0]
	v_pk_mul_f32 v[48:49], v[48:49], v[50:51]
	v_pk_mul_f32 v[50:51], v[44:45], s[22:23] op_sel_hi:[1,0]
	v_exp_f32_e32 v54, v54
	v_exp_f32_e32 v55, v55
	v_exp_f32_e32 v16, v16
	v_exp_f32_e32 v14, v14
	v_exp_f32_e32 v15, v15
	v_exp_f32_e32 v17, v17
	v_exp_f32_e32 v60, v60
	v_exp_f32_e32 v58, v58
	v_exp_f32_e32 v59, v59
	v_exp_f32_e32 v61, v61
	v_exp_f32_e32 v50, v50
	v_exp_f32_e32 v51, v51
	v_exp_f32_e32 v20, v20
	v_exp_f32_e32 v18, v18
	v_exp_f32_e32 v19, v19
	v_exp_f32_e32 v21, v21
	v_pk_add_f32 v[54:55], v[54:55], 1.0 op_sel_hi:[1,0]
	v_pk_add_f32 v[14:15], v[14:15], 1.0 op_sel_hi:[1,0]
	v_pk_add_f32 v[16:17], v[16:17], 1.0 op_sel_hi:[1,0]
	v_pk_add_f32 v[58:59], v[58:59], 1.0 op_sel_hi:[1,0]
	v_pk_add_f32 v[60:61], v[60:61], 1.0 op_sel_hi:[1,0]
	v_pk_add_f32 v[50:51], v[50:51], 1.0 op_sel_hi:[1,0]
	v_rcp_f32_e32 v54, v54
	v_rcp_f32_e32 v55, v55
	v_pk_add_f32 v[18:19], v[18:19], 1.0 op_sel_hi:[1,0]
	v_pk_add_f32 v[20:21], v[20:21], 1.0 op_sel_hi:[1,0]
	v_rcp_f32_e32 v16, v16
	v_rcp_f32_e32 v14, v14
	v_rcp_f32_e32 v15, v15
	v_rcp_f32_e32 v17, v17
	v_rcp_f32_e32 v60, v60
	v_rcp_f32_e32 v61, v61
	v_rcp_f32_e32 v58, v58
	v_rcp_f32_e32 v59, v59
	v_rcp_f32_e32 v50, v50
	v_rcp_f32_e32 v51, v51
	v_pk_mul_f32 v[2:3], v[2:3], v[22:23]
	v_rcp_f32_e32 v20, v20
	v_rcp_f32_e32 v21, v21
	v_rcp_f32_e32 v18, v18
	v_rcp_f32_e32 v19, v19
	v_pk_mul_f32 v[4:5], v[26:27], v[4:5] op_sel_hi:[0,1]
	v_pk_mul_f32 v[2:3], v[26:27], v[2:3] op_sel_hi:[0,1]
	v_pk_mul_f32 v[42:43], v[42:43], v[52:53]
	v_pk_mul_f32 v[2:3], v[10:11], v[2:3]
	v_pk_mul_f32 v[4:5], v[12:13], v[4:5]
	v_lshl_add_u64 v[56:57], v[56:57], 0, v[30:31]
	v_pk_mul_f32 v[32:33], v[44:45], v[32:33]
	v_pk_mul_f32 v[44:45], v[42:43], v[54:55]
	v_lshl_add_u64 v[28:29], v[28:29], 0, v[30:31]
	v_pk_mul_f32 v[10:11], v[4:5], v[14:15]
	v_pk_mul_f32 v[4:5], v[2:3], v[16:17]
	s_andn2_b64 vcc, exec, s[4:5]
	s_mov_b64 s[0:1], -1
	v_pk_mul_f32 v[48:49], v[48:49], v[58:59]
	v_pk_mul_f32 v[46:47], v[46:47], v[60:61]
	v_pk_mul_f32 v[32:33], v[32:33], v[50:51]
	v_cvt_pk_bf16_f32 v42, v46, v47
	v_cvt_pk_bf16_f32 v43, v48, v49
	v_cvt_pk_bf16_f32 v44, v44, v45
	v_pk_mul_f32 v[8:9], v[8:9], v[18:19]
	v_cvt_pk_bf16_f32 v45, v32, v33
	global_store_dwordx4 v[56:57], v[42:45], off sc1
	v_pk_mul_f32 v[6:7], v[6:7], v[20:21]
	s_nop 0
	v_cvt_pk_bf16_f32 v2, v6, v7
	v_cvt_pk_bf16_f32 v3, v8, v9
	v_cvt_pk_bf16_f32 v4, v4, v5
	v_cvt_pk_bf16_f32 v5, v10, v11
	global_store_dwordx4 v[28:29], v[2:5], off sc1
	s_cbranch_vccnz .LBB0_1068
	s_andn2_b64 vcc, exec, s[6:7]
	s_cbranch_vccnz .LBB0_1067
	s_barrier
	s_branch .LBB0_1067
